# in-proj: the 8 padding N-tiles per XCD (24 valid columns) moved to the last tile slots so they pair with full fourth-round tiles; their waves skip MFMAs and fragment reads of all-padding column blocks
# speedup vs baseline: 1.1649x; 1.0039x over previous
; __device__ void phase_inproj(const Params& p, int layer, unsigned char* smem) {
;     ...
;   for (int idx = loc; idx < 8 * NT_IN; idx += nloc) {
;     int grp = idx / (2 * NT_IN), within = idx % (2 * NT_IN);
;     int nt = within >> 1, mt = xcd * 8 + grp * 2 + (within & 1);
;     int vbase = -1;
;     if (nt == 4) vbase = 0; else if (nt == 5) vbase = 128; else if (nt == 11) vbase = 256;
;     else if (nt == 21) vbase = 384; else if (nt == 23) vbase = 512;
;     if (vbase >= 0) gemm_tile2<1>(P_XN, DM, W, DM, DM, mt * 256, nt * 128, P_VT, vbase, nullptr, nullptr, smem);
;     else gemm_tile2<0>(P_XN, DM, W, DM, DM, mt * 256, nt * 128, P_H, 0, nullptr, nullptr, smem);
.LBB0_287:
	s_cmpk_lt_u32 s29, 0xe0
	s_cbranch_scc0 .Ltile_pad
	s_lshr_b32 s0, s29, 3
	s_mul_i32 s0, s0, 37
	s_lshr_b32 s25, s0, 8
	s_mul_i32 s0, s25, 56
	s_sub_i32 s24, s29, s0
	s_branch .Ltile_dec
.Ltile_pad:
	s_sub_i32 s0, s29, 0xe0
	s_lshr_b32 s25, s0, 1
	s_and_b32 s24, s0, 1
	s_add_i32 s24, s24, 56
.Ltile_dec:
	s_bfe_u32 s31, s24, 0x70001
	s_cmp_lt_i32 s31, 11
	s_cbranch_scc1 .LBB0_292
	s_cmp_gt_i32 s31, 20
	s_cbranch_scc0 .LBB0_293
	s_cmp_gt_i32 s31, 22
	s_cbranch_scc0 .LBB0_294
	s_mov_b64 s[6:7], -1
	s_mov_b64 s[18:19], 0
	s_cmp_eq_u32 s31, 23
	s_mov_b64 s[0:1], 0
	s_cbranch_scc0 .LBB0_295
	s_mov_b64 s[6:7], 0
	s_mov_b64 s[0:1], -1
	s_branch .LBB0_295

; __device__ __forceinline__ int otid() { int t = threadIdx.x; asm volatile("" : "+v"(t)); return t; }
; template <int MODE>
; __device__ void gemm_tile2(const u16* __restrict__ X, int lda, const u16* __restrict__ W, int ldb, int K,
;                            int m0, int n0, u16* __restrict__ outb, int vbase,
;                            const float* resid, float* outf, unsigned char* smem) {
;     ...
;   const int tid = otid(), lane = tid & 63, l15 = lane & 15, quad = lane >> 4;
;   const int wave = tid >> 6;
;   const int wx = wave >> 1, ww = wave & 1;
;   f32x4 acc[8][4];
; #pragma unroll
;   for (int i = 0; i < 8; ++i)
; #pragma unroll
;     for (int j = 0; j < 4; ++j) acc[i][j] = f32x4{0.f, 0.f, 0.f, 0.f};
;   u32x4 rx[2][4], rw[2][2];
;   const int lrow = tid >> 2, lkc = (tid & 3) * 8;
;   const int lsw = ((tid & 3) ^ ((0 - (lrow >> 2)) & 3)) * 8;
;   const int fsw = (quad ^ ((0 - (l15 >> 2)) & 3)) * 8;
;   const auto rsX = __builtin_amdgcn_make_buffer_rsrc((void*)(X + (size_t)m0 * lda), (short)0, 0x7fffffff, 0x00020000);
;   const auto rsW = __builtin_amdgcn_make_buffer_rsrc((void*)(W + (size_t)n0 * ldb), (short)0, 0x7fffffff, 0x00020000);
;   const int vox = (lrow * lda + lkc) * 2, vow = (lrow * ldb + lkc) * 2;
;   const int nk = K / 32;
;     ...
;   G2_GLOAD(0, 0);
;   G2_GLOAD(1, 1);
;   __syncthreads();
;   G2_LSTORE(0, 0);
;   G2_GLOAD(0, 2);
;   __syncthreads();
.LBB0_312:
	v_mov_b32_e32 v0, v210
	s_lshl_b32 s0, s31, 7
	s_lshl_b32 s6, s18, 19
	s_add_u32 s24, s36, s6
	s_addc_u32 s6, s37, 0
	s_and_b32 s25, s6, 0xffff
	s_lshl_b32 s6, s31, 18
	s_add_u32 s40, s8, s6
	s_addc_u32 s6, s9, 0
	s_and_b32 s41, s6, 0xffff
	s_mov_b32 s42, s26
	s_mov_b32 s43, s27
	v_lshlrev_b32_e32 v230, 4, v0
	v_lshrrev_b32_e32 v231, 4, v0
	v_bfe_u32 v233, v0, 6, 1
	s_cmp_lg_u32 s31, 28
	s_cbranch_scc1 .Lf0_full
	s_nop 1
	v_readfirstlane_b32 s6, v233
	s_cmp_eq_u32 s6, 1
	s_cbranch_scc1 .Lf0_none
	v_lshrrev_b32_e32 v2, 2, v0
	v_sub_u32_e32 v2, 0, v2
	v_lshrrev_b32_e32 v3, 4, v0
	v_xor_b32_e32 v2, v3, v2
	v_lshlrev_b32_e32 v2, 4, v2
	v_and_b32_e32 v2, 48, v2
	v_lshlrev_b32_e32 v4, 6, v0
	v_and_b32_e32 v5, 0x3c0, v4
	v_bfe_u32 v6, v0, 6, 1
	v_lshl_or_b32 v6, v6, 12, v2
	v_add_u32_e32 v235, v6, v5
	v_and_b32_e32 v4, 0xffffe3c0, v4
	v_add_u32_e32 v236, v2, v4
	v_xor_b32_e32 v232, 64, v235
	v_add_u32_e32 v232, 0x6000, v232
	v_xor_b32_e32 v237, 64, v236
	v_add_u32_e32 v237, 0x6000, v237
	v_and_b32_e32 v2, 3, v0
	v_bfe_u32 v221, v0, 2, 1
	v_lshrrev_b32_e32 v4, 3, v0
	v_lshrrev_b32_e32 v5, 2, v4
	v_sub_u32_e32 v5, 0, v5
	v_and_b32_e32 v5, 3, v5
	v_xor_b32_e32 v5, v2, v5
	v_lshlrev_b32_e32 v5, 4, v5
	v_lshl_or_b32 v5, v221, 6, v5
	v_lshl_or_b32 v218, v4, 11, v5
	v_add_u32_e32 v219, 0x10000, v218
	v_lshlrev_b32_e32 v2, 4, v2
	v_xor_b32_e32 v4, v4, v221
	v_lshl_or_b32 v220, v4, 6, v2
	buffer_load_dwordx4 v[2:5], v218, s[24:27], 0 offen
	buffer_load_dwordx4 v[6:9], v219, s[24:27], 0 offen
	buffer_load_dwordx4 v[10:13], v218, s[24:27], s27 offen
	buffer_load_dwordx4 v[14:17], v219, s[24:27], s27 offen
	buffer_load_dwordx4 v[18:21], v218, s[24:27], s77 offen
	buffer_load_dwordx4 v[22:25], v219, s[24:27], s77 offen
	buffer_load_dwordx4 v[26:29], v218, s[24:27], s78 offen
	buffer_load_dwordx4 v[30:33], v219, s[24:27], s78 offen
	buffer_load_dwordx4 v[34:37], v218, s[40:43], 0 offen
	buffer_load_dwordx4 v[38:41], v219, s[40:43], 0 offen
	buffer_load_dwordx4 v[42:45], v218, s[40:43], s27 offen
	buffer_load_dwordx4 v[46:49], v219, s[40:43], s27 offen
	v_add_u32_e32 v218, 0x80, v218
	v_add_u32_e32 v219, 0x80, v219
	v_mov_b32_e32 v50, 0
	v_mov_b32_e32 v51, 0
	v_mov_b32_e32 v52, 0
	v_mov_b32_e32 v53, 0
	v_mov_b32_e32 v54, 0
	v_mov_b32_e32 v55, 0
	v_mov_b32_e32 v56, 0
	v_mov_b32_e32 v57, 0
	v_mov_b32_e32 v58, 0
	v_mov_b32_e32 v59, 0
	v_mov_b32_e32 v60, 0
	v_mov_b32_e32 v61, 0
	v_mov_b32_e32 v62, 0
	v_mov_b32_e32 v63, 0
	v_mov_b32_e32 v64, 0
	v_mov_b32_e32 v65, 0
	v_mov_b32_e32 v66, 0
	v_mov_b32_e32 v67, 0
	v_mov_b32_e32 v68, 0
	v_mov_b32_e32 v69, 0
	v_mov_b32_e32 v70, 0
	v_mov_b32_e32 v71, 0
	v_mov_b32_e32 v72, 0
	v_mov_b32_e32 v73, 0
	v_mov_b32_e32 v74, 0
	v_mov_b32_e32 v75, 0
	v_mov_b32_e32 v76, 0
	v_mov_b32_e32 v77, 0
	v_mov_b32_e32 v78, 0
	v_mov_b32_e32 v79, 0
	v_mov_b32_e32 v80, 0
	v_mov_b32_e32 v81, 0
	v_mov_b32_e32 v82, 0
	v_mov_b32_e32 v83, 0
	v_mov_b32_e32 v84, 0
	v_mov_b32_e32 v85, 0
	v_mov_b32_e32 v86, 0
	v_mov_b32_e32 v87, 0
	v_mov_b32_e32 v88, 0
	v_mov_b32_e32 v89, 0
	v_mov_b32_e32 v90, 0
	v_mov_b32_e32 v91, 0
	v_mov_b32_e32 v92, 0
	v_mov_b32_e32 v93, 0
	v_mov_b32_e32 v94, 0
	v_mov_b32_e32 v95, 0
	v_mov_b32_e32 v96, 0
	v_mov_b32_e32 v97, 0
	v_mov_b32_e32 v98, 0
	v_mov_b32_e32 v99, 0
	v_mov_b32_e32 v100, 0
	v_mov_b32_e32 v101, 0
	v_mov_b32_e32 v102, 0
	v_mov_b32_e32 v103, 0
	v_mov_b32_e32 v104, 0
	v_mov_b32_e32 v105, 0
	v_mov_b32_e32 v106, 0
	v_mov_b32_e32 v107, 0
	v_mov_b32_e32 v108, 0
	v_mov_b32_e32 v109, 0
	v_mov_b32_e32 v110, 0
	v_mov_b32_e32 v111, 0
	v_mov_b32_e32 v112, 0
	v_mov_b32_e32 v113, 0
	v_mov_b32_e32 v114, 0
	v_mov_b32_e32 v115, 0
	v_mov_b32_e32 v116, 0
	v_mov_b32_e32 v117, 0
	v_mov_b32_e32 v118, 0
	v_mov_b32_e32 v119, 0
	v_mov_b32_e32 v120, 0
	v_mov_b32_e32 v121, 0
	v_mov_b32_e32 v122, 0
	v_mov_b32_e32 v123, 0
	v_mov_b32_e32 v124, 0
	v_mov_b32_e32 v125, 0
	v_mov_b32_e32 v126, 0
	v_mov_b32_e32 v127, 0
	v_mov_b32_e32 v128, 0
	v_mov_b32_e32 v129, 0
	v_mov_b32_e32 v130, 0
	v_mov_b32_e32 v131, 0
	v_mov_b32_e32 v132, 0
	v_mov_b32_e32 v133, 0
	v_mov_b32_e32 v134, 0
	v_mov_b32_e32 v135, 0
	v_mov_b32_e32 v136, 0
	v_mov_b32_e32 v137, 0
	v_mov_b32_e32 v138, 0
	v_mov_b32_e32 v139, 0
	v_mov_b32_e32 v140, 0
	v_mov_b32_e32 v141, 0
	v_mov_b32_e32 v142, 0
	v_mov_b32_e32 v143, 0
	v_mov_b32_e32 v144, 0
	v_mov_b32_e32 v145, 0
	v_mov_b32_e32 v146, 0
	v_mov_b32_e32 v147, 0
	v_mov_b32_e32 v148, 0
	v_mov_b32_e32 v149, 0
	v_mov_b32_e32 v150, 0
	v_mov_b32_e32 v151, 0
	v_mov_b32_e32 v152, 0
	v_mov_b32_e32 v153, 0
	v_mov_b32_e32 v154, 0
	v_mov_b32_e32 v155, 0
	v_mov_b32_e32 v156, 0
	v_mov_b32_e32 v157, 0
	v_mov_b32_e32 v158, 0
	v_mov_b32_e32 v159, 0
	v_mov_b32_e32 v160, 0
	v_mov_b32_e32 v161, 0
	v_mov_b32_e32 v162, 0
	v_mov_b32_e32 v163, 0
	v_mov_b32_e32 v164, 0
	v_mov_b32_e32 v165, 0
	v_mov_b32_e32 v166, 0
	v_mov_b32_e32 v167, 0
	v_mov_b32_e32 v168, 0
	v_mov_b32_e32 v169, 0
	v_mov_b32_e32 v170, 0
	v_mov_b32_e32 v171, 0
	v_mov_b32_e32 v172, 0
	v_mov_b32_e32 v173, 0
	v_mov_b32_e32 v174, 0
	v_mov_b32_e32 v175, 0
	v_mov_b32_e32 v176, 0
	v_mov_b32_e32 v177, 0
	s_mov_b32 s6, 0
	s_mov_b32 s7, 0x6000
	s_mov_b32 s35, 0xc000
	s_mov_b32 s1, 0
	v_mad_i32_i24 v234, v221, s7, v220
	s_barrier
	s_waitcnt vmcnt(11)
	ds_write_b128 v234, v[2:5]
	s_waitcnt vmcnt(10)
	ds_write_b128 v234, v[6:9] offset:2048
	s_waitcnt vmcnt(9)
	ds_write_b128 v234, v[10:13] offset:4096
	s_waitcnt vmcnt(8)
	ds_write_b128 v234, v[14:17] offset:6144
	s_waitcnt vmcnt(7)
	ds_write_b128 v234, v[18:21] offset:8192
	s_waitcnt vmcnt(6)
	ds_write_b128 v234, v[22:25] offset:10240
	s_waitcnt vmcnt(5)
	ds_write_b128 v234, v[26:29] offset:12288
	s_waitcnt vmcnt(4)
	ds_write_b128 v234, v[30:33] offset:14336
	s_waitcnt vmcnt(3)
	ds_write_b128 v234, v[34:37] offset:16384
	s_waitcnt vmcnt(2)
	ds_write_b128 v234, v[38:41] offset:18432
	s_waitcnt vmcnt(1)
	ds_write_b128 v234, v[42:45] offset:20480
	s_waitcnt vmcnt(0)
	ds_write_b128 v234, v[46:49] offset:22528
	buffer_load_dwordx4 v[2:5], v218, s[24:27], 0 offen
	buffer_load_dwordx4 v[6:9], v219, s[24:27], 0 offen
	buffer_load_dwordx4 v[10:13], v218, s[24:27], s27 offen
	buffer_load_dwordx4 v[14:17], v219, s[24:27], s27 offen
	buffer_load_dwordx4 v[18:21], v218, s[24:27], s77 offen
	buffer_load_dwordx4 v[22:25], v219, s[24:27], s77 offen
	buffer_load_dwordx4 v[26:29], v218, s[24:27], s78 offen
	buffer_load_dwordx4 v[30:33], v219, s[24:27], s78 offen
	buffer_load_dwordx4 v[34:37], v218, s[40:43], 0 offen
	buffer_load_dwordx4 v[38:41], v219, s[40:43], 0 offen
	buffer_load_dwordx4 v[42:45], v218, s[40:43], s27 offen
	buffer_load_dwordx4 v[46:49], v219, s[40:43], s27 offen
	v_add_u32_e32 v218, 0x80, v218
	v_add_u32_e32 v219, 0x80, v219
	s_waitcnt lgkmcnt(0)
	s_barrier
	ds_read_b128 v[178:181], v235 offset:16384
	ds_read_b128 v[182:185], v235 offset:17408
	ds_read_b128 v[194:197], v236
	ds_read_b128 v[198:201], v236 offset:1024
	ds_read_b128 v[202:205], v236 offset:2048
	ds_read_b128 v[206:209], v236 offset:3072
; template <int MODE>
; __device__ void gemm_tile2(const u16* __restrict__ X, int lda, const u16* __restrict__ W, int ldb, int K,
;                            int m0, int n0, u16* __restrict__ outb, int vbase,
;                            const float* resid, float* outf, unsigned char* smem) {
;     ...
;   for (int kt2 = 0; kt2 < nk; kt2 += 2) {
; #pragma unroll
;     for (int h = 0; h < 2; ++h) {
;       const int kt = kt2 + h;
;       const u16* st = sbase + h * G2STAGE;
;       bf16x8 fw[4], fx[4];
; #pragma unroll
;       for (int j = 0; j < 4; ++j) fw[j] = *(const bf16x8*)(st + 256 * G2S + (ww * 64 + j * 16 + l15) * G2S + fsw);
; #pragma unroll
;       for (int i = 0; i < 4; ++i) fx[i] = *(const bf16x8*)(st + (wx * 128 + i * 16 + l15) * G2S + fsw);
;       __builtin_amdgcn_sched_barrier(0);
;       __builtin_amdgcn_s_setprio(1);
; #pragma unroll
;       for (int i = 0; i < 4; ++i) {
; #pragma unroll
;         for (int j = 0; j < 4; ++j) {
;           if (MODE == 1) acc[i][j] = mfma16(fx[i], fw[j], acc[i][j]);
;           else acc[i][j] = mfma16(fw[j], fx[i], acc[i][j]);
;         }
;       }
;       __builtin_amdgcn_s_setprio(0);
;       __builtin_amdgcn_sched_barrier(0);
; #pragma unroll
;       for (int i = 0; i < 4; ++i) fx[i] = *(const bf16x8*)(st + (wx * 128 + (i + 4) * 16 + l15) * G2S + fsw);
;       __builtin_amdgcn_sched_barrier(0);
;       if (kt + 1 < nk) G2_LSTORE(1 - h, 1 - h);
;       if (kt + 3 < nk) G2_GLOAD(1 - h, kt + 3);
;       __builtin_amdgcn_sched_barrier(0);
;       __builtin_amdgcn_s_setprio(1);
; #pragma unroll
;       for (int i = 0; i < 4; ++i) {
; #pragma unroll
;         for (int j = 0; j < 4; ++j) {
;           if (MODE == 1) acc[i + 4][j] = mfma16(fx[i], fw[j], acc[i + 4][j]);
;           else acc[i + 4][j] = mfma16(fw[j], fx[i], acc[i + 4][j]);
;         }
;       }
;       __builtin_amdgcn_s_setprio(0);
;       __syncthreads();
;     }
.Lf0h_loop:
	s_waitcnt lgkmcnt(3)
	v_mfma_f32_16x16x32_bf16 v[174:177], v[178:181], v[194:197], v[174:177]
	v_mfma_f32_16x16x32_bf16 v[170:173], v[182:185], v[194:197], v[170:173]
	ds_read_b128 v[194:197], v236 offset:4096
	ds_read_b128 v[238:241], v232 offset:16384
	s_waitcnt lgkmcnt(4)
	v_mfma_f32_16x16x32_bf16 v[158:161], v[178:181], v[198:201], v[158:161]
	v_mfma_f32_16x16x32_bf16 v[154:157], v[182:185], v[198:201], v[154:157]
	ds_read_b128 v[198:201], v236 offset:5120
	ds_read_b128 v[242:245], v232 offset:17408
	s_waitcnt lgkmcnt(5)
	v_mfma_f32_16x16x32_bf16 v[142:145], v[178:181], v[202:205], v[142:145]
	v_mfma_f32_16x16x32_bf16 v[138:141], v[182:185], v[202:205], v[138:141]
	ds_read_b128 v[202:205], v236 offset:6144
	s_waitcnt lgkmcnt(5)
	v_mfma_f32_16x16x32_bf16 v[126:129], v[178:181], v[206:209], v[126:129]
	v_mfma_f32_16x16x32_bf16 v[122:125], v[182:185], v[206:209], v[122:125]
	ds_read_b128 v[206:209], v236 offset:7168
	s_sub_i32 s38, s35, s6
	v_add_u32_e32 v235, s38, v235
	v_add_u32_e32 v236, s38, v236
	s_sub_i32 s38, s6, s35
	v_mad_i32_i24 v234, v221, s38, v220
	v_add_u32_e32 v234, s35, v234
	s_waitcnt lgkmcnt(0)
	s_barrier
	s_setprio 1
	v_mfma_f32_16x16x32_bf16 v[110:113], v[178:181], v[194:197], v[110:113]
	v_mfma_f32_16x16x32_bf16 v[106:109], v[182:185], v[194:197], v[106:109]
	ds_read_b128 v[194:197], v237
	s_waitcnt vmcnt(11)
	ds_write_b128 v234, v[2:5]
	buffer_load_dwordx4 v[2:5], v218, s[24:27], 0 offen
	v_mfma_f32_16x16x32_bf16 v[94:97], v[178:181], v[198:201], v[94:97]
	v_mfma_f32_16x16x32_bf16 v[90:93], v[182:185], v[198:201], v[90:93]
	ds_read_b128 v[198:201], v237 offset:1024
	s_waitcnt vmcnt(11)
	ds_write_b128 v234, v[6:9] offset:2048
	buffer_load_dwordx4 v[6:9], v219, s[24:27], 0 offen
	v_mfma_f32_16x16x32_bf16 v[78:81], v[178:181], v[202:205], v[78:81]
	v_mfma_f32_16x16x32_bf16 v[74:77], v[182:185], v[202:205], v[74:77]
	ds_read_b128 v[202:205], v237 offset:2048
	s_waitcnt vmcnt(11)
	ds_write_b128 v234, v[10:13] offset:4096
	buffer_load_dwordx4 v[10:13], v218, s[24:27], s27 offen
	v_mfma_f32_16x16x32_bf16 v[62:65], v[178:181], v[206:209], v[62:65]
	v_mfma_f32_16x16x32_bf16 v[58:61], v[182:185], v[206:209], v[58:61]
	ds_read_b128 v[206:209], v237 offset:3072
	s_waitcnt vmcnt(11)
	ds_write_b128 v234, v[14:17] offset:6144
	buffer_load_dwordx4 v[14:17], v219, s[24:27], s27 offen
	s_waitcnt lgkmcnt(7)
	v_mfma_f32_16x16x32_bf16 v[174:177], v[238:241], v[194:197], v[174:177]
	v_mfma_f32_16x16x32_bf16 v[170:173], v[242:245], v[194:197], v[170:173]
	ds_read_b128 v[194:197], v237 offset:4096
	s_waitcnt vmcnt(11)
	ds_write_b128 v234, v[18:21] offset:8192
	buffer_load_dwordx4 v[18:21], v218, s[24:27], s77 offen
	s_waitcnt lgkmcnt(7)
	v_mfma_f32_16x16x32_bf16 v[158:161], v[238:241], v[198:201], v[158:161]
	v_mfma_f32_16x16x32_bf16 v[154:157], v[242:245], v[198:201], v[154:157]
	ds_read_b128 v[198:201], v237 offset:5120
	s_waitcnt vmcnt(11)
	ds_write_b128 v234, v[22:25] offset:10240
	buffer_load_dwordx4 v[22:25], v219, s[24:27], s77 offen
	s_waitcnt lgkmcnt(7)
	v_mfma_f32_16x16x32_bf16 v[142:145], v[238:241], v[202:205], v[142:145]
	v_mfma_f32_16x16x32_bf16 v[138:141], v[242:245], v[202:205], v[138:141]
	ds_read_b128 v[202:205], v237 offset:6144
	s_waitcnt vmcnt(11)
	ds_write_b128 v234, v[26:29] offset:12288
	buffer_load_dwordx4 v[26:29], v218, s[24:27], s78 offen
	s_waitcnt lgkmcnt(7)
	v_mfma_f32_16x16x32_bf16 v[126:129], v[238:241], v[206:209], v[126:129]
	v_mfma_f32_16x16x32_bf16 v[122:125], v[242:245], v[206:209], v[122:125]
	ds_read_b128 v[206:209], v237 offset:7168
	s_sub_i32 s38, s6, s7
	v_add_u32_e32 v232, s38, v232
	v_add_u32_e32 v237, s38, v237
	s_waitcnt vmcnt(11)
	ds_write_b128 v234, v[30:33] offset:14336
	buffer_load_dwordx4 v[30:33], v219, s[24:27], s78 offen
	s_waitcnt lgkmcnt(7)
	v_mfma_f32_16x16x32_bf16 v[110:113], v[238:241], v[194:197], v[110:113]
	v_mfma_f32_16x16x32_bf16 v[106:109], v[242:245], v[194:197], v[106:109]
	s_waitcnt vmcnt(11)
	ds_write_b128 v234, v[34:37] offset:16384
	buffer_load_dwordx4 v[34:37], v218, s[40:43], 0 offen
	s_waitcnt lgkmcnt(6)
	v_mfma_f32_16x16x32_bf16 v[94:97], v[238:241], v[198:201], v[94:97]
	v_mfma_f32_16x16x32_bf16 v[90:93], v[242:245], v[198:201], v[90:93]
	s_waitcnt vmcnt(11)
	ds_write_b128 v234, v[38:41] offset:18432
	buffer_load_dwordx4 v[38:41], v219, s[40:43], 0 offen
	s_waitcnt lgkmcnt(5)
	v_mfma_f32_16x16x32_bf16 v[78:81], v[238:241], v[202:205], v[78:81]
	v_mfma_f32_16x16x32_bf16 v[74:77], v[242:245], v[202:205], v[74:77]
	s_waitcnt vmcnt(11)
	ds_write_b128 v234, v[42:45] offset:20480
	buffer_load_dwordx4 v[42:45], v218, s[40:43], s27 offen
	s_waitcnt lgkmcnt(4)
	v_mfma_f32_16x16x32_bf16 v[62:65], v[238:241], v[206:209], v[62:65]
	v_mfma_f32_16x16x32_bf16 v[58:61], v[242:245], v[206:209], v[58:61]
	s_waitcnt vmcnt(11)
	ds_write_b128 v234, v[46:49] offset:22528
	buffer_load_dwordx4 v[46:49], v219, s[40:43], s27 offen
	v_add_u32_e32 v218, 0x80, v218
	v_add_u32_e32 v219, 0x80, v219
	s_waitcnt lgkmcnt(0)
	s_setprio 0
	s_barrier
	s_mov_b32 s38, s35
	s_mov_b32 s35, s7
	s_mov_b32 s7, s6
	s_mov_b32 s6, s38
	ds_read_b128 v[178:181], v235 offset:16384
	ds_read_b128 v[182:185], v235 offset:17408
	ds_read_b128 v[194:197], v236
	ds_read_b128 v[198:201], v236 offset:1024
	ds_read_b128 v[202:205], v236 offset:2048
	ds_read_b128 v[206:209], v236 offset:3072
	s_add_u32 s1, s1, 1
	s_cmp_lt_u32 s1, 14
	s_cbranch_scc1 .Lf0h_loop
; template <int MODE>
; __device__ void gemm_tile2(const u16* __restrict__ X, int lda, const u16* __restrict__ W, int ldb, int K,
;                            int m0, int n0, u16* __restrict__ outb, int vbase,
;                            const float* resid, float* outf, unsigned char* smem) {
;     ...
;   for (int kt2 = 0; kt2 < nk; kt2 += 2) {
; #pragma unroll
;     for (int h = 0; h < 2; ++h) {
;       const int kt = kt2 + h;
;       const u16* st = sbase + h * G2STAGE;
;       bf16x8 fw[4], fx[4];
; #pragma unroll
;       for (int j = 0; j < 4; ++j) fw[j] = *(const bf16x8*)(st + 256 * G2S + (ww * 64 + j * 16 + l15) * G2S + fsw);
; #pragma unroll
;       for (int i = 0; i < 4; ++i) fx[i] = *(const bf16x8*)(st + (wx * 128 + i * 16 + l15) * G2S + fsw);
;       __builtin_amdgcn_sched_barrier(0);
;       __builtin_amdgcn_s_setprio(1);
; #pragma unroll
;       for (int i = 0; i < 4; ++i) {
; #pragma unroll
;         for (int j = 0; j < 4; ++j) {
;           if (MODE == 1) acc[i][j] = mfma16(fx[i], fw[j], acc[i][j]);
;           else acc[i][j] = mfma16(fw[j], fx[i], acc[i][j]);
;         }
;       }
;       __builtin_amdgcn_s_setprio(0);
;       __builtin_amdgcn_sched_barrier(0);
; #pragma unroll
;       for (int i = 0; i < 4; ++i) fx[i] = *(const bf16x8*)(st + (wx * 128 + (i + 4) * 16 + l15) * G2S + fsw);
;       __builtin_amdgcn_sched_barrier(0);
;       if (kt + 1 < nk) G2_LSTORE(1 - h, 1 - h);
;       if (kt + 3 < nk) G2_GLOAD(1 - h, kt + 3);
;       __builtin_amdgcn_sched_barrier(0);
;       __builtin_amdgcn_s_setprio(1);
; #pragma unroll
;       for (int i = 0; i < 4; ++i) {
; #pragma unroll
;         for (int j = 0; j < 4; ++j) {
;           if (MODE == 1) acc[i + 4][j] = mfma16(fx[i], fw[j], acc[i + 4][j]);
;           else acc[i + 4][j] = mfma16(fw[j], fx[i], acc[i + 4][j]);
;         }
;       }
;       __builtin_amdgcn_s_setprio(0);
;       __syncthreads();
;     }
	s_waitcnt lgkmcnt(3)
	v_mfma_f32_16x16x32_bf16 v[174:177], v[178:181], v[194:197], v[174:177]
	v_mfma_f32_16x16x32_bf16 v[170:173], v[182:185], v[194:197], v[170:173]
	ds_read_b128 v[194:197], v236 offset:4096
	ds_read_b128 v[238:241], v232 offset:16384
	s_waitcnt lgkmcnt(4)
	v_mfma_f32_16x16x32_bf16 v[158:161], v[178:181], v[198:201], v[158:161]
	v_mfma_f32_16x16x32_bf16 v[154:157], v[182:185], v[198:201], v[154:157]
	ds_read_b128 v[198:201], v236 offset:5120
	ds_read_b128 v[242:245], v232 offset:17408
	s_waitcnt lgkmcnt(5)
	v_mfma_f32_16x16x32_bf16 v[142:145], v[178:181], v[202:205], v[142:145]
	v_mfma_f32_16x16x32_bf16 v[138:141], v[182:185], v[202:205], v[138:141]
	ds_read_b128 v[202:205], v236 offset:6144
	s_waitcnt lgkmcnt(5)
	v_mfma_f32_16x16x32_bf16 v[126:129], v[178:181], v[206:209], v[126:129]
	v_mfma_f32_16x16x32_bf16 v[122:125], v[182:185], v[206:209], v[122:125]
	ds_read_b128 v[206:209], v236 offset:7168
	s_sub_i32 s38, s35, s6
	v_add_u32_e32 v235, s38, v235
	v_add_u32_e32 v236, s38, v236
	s_sub_i32 s38, s6, s35
	v_mad_i32_i24 v234, v221, s38, v220
	v_add_u32_e32 v234, s35, v234
	s_waitcnt lgkmcnt(0)
	s_barrier
	s_setprio 1
	v_mfma_f32_16x16x32_bf16 v[110:113], v[178:181], v[194:197], v[110:113]
	v_mfma_f32_16x16x32_bf16 v[106:109], v[182:185], v[194:197], v[106:109]
	ds_read_b128 v[194:197], v237
	s_waitcnt vmcnt(11)
	ds_write_b128 v234, v[2:5]
	v_mfma_f32_16x16x32_bf16 v[94:97], v[178:181], v[198:201], v[94:97]
	v_mfma_f32_16x16x32_bf16 v[90:93], v[182:185], v[198:201], v[90:93]
	ds_read_b128 v[198:201], v237 offset:1024
	s_waitcnt vmcnt(10)
	ds_write_b128 v234, v[6:9] offset:2048
	v_mfma_f32_16x16x32_bf16 v[78:81], v[178:181], v[202:205], v[78:81]
	v_mfma_f32_16x16x32_bf16 v[74:77], v[182:185], v[202:205], v[74:77]
	ds_read_b128 v[202:205], v237 offset:2048
	s_waitcnt vmcnt(9)
	ds_write_b128 v234, v[10:13] offset:4096
	v_mfma_f32_16x16x32_bf16 v[62:65], v[178:181], v[206:209], v[62:65]
	v_mfma_f32_16x16x32_bf16 v[58:61], v[182:185], v[206:209], v[58:61]
	ds_read_b128 v[206:209], v237 offset:3072
	s_waitcnt vmcnt(8)
	ds_write_b128 v234, v[14:17] offset:6144
	s_waitcnt lgkmcnt(7)
	v_mfma_f32_16x16x32_bf16 v[174:177], v[238:241], v[194:197], v[174:177]
	v_mfma_f32_16x16x32_bf16 v[170:173], v[242:245], v[194:197], v[170:173]
	ds_read_b128 v[194:197], v237 offset:4096
	s_waitcnt vmcnt(7)
	ds_write_b128 v234, v[18:21] offset:8192
	s_waitcnt lgkmcnt(7)
	v_mfma_f32_16x16x32_bf16 v[158:161], v[238:241], v[198:201], v[158:161]
	v_mfma_f32_16x16x32_bf16 v[154:157], v[242:245], v[198:201], v[154:157]
	ds_read_b128 v[198:201], v237 offset:5120
	s_waitcnt vmcnt(6)
	ds_write_b128 v234, v[22:25] offset:10240
	s_waitcnt lgkmcnt(7)
	v_mfma_f32_16x16x32_bf16 v[142:145], v[238:241], v[202:205], v[142:145]
	v_mfma_f32_16x16x32_bf16 v[138:141], v[242:245], v[202:205], v[138:141]
	ds_read_b128 v[202:205], v237 offset:6144
	s_waitcnt vmcnt(5)
	ds_write_b128 v234, v[26:29] offset:12288
	s_waitcnt lgkmcnt(7)
	v_mfma_f32_16x16x32_bf16 v[126:129], v[238:241], v[206:209], v[126:129]
	v_mfma_f32_16x16x32_bf16 v[122:125], v[242:245], v[206:209], v[122:125]
	ds_read_b128 v[206:209], v237 offset:7168
	s_sub_i32 s38, s6, s7
	v_add_u32_e32 v232, s38, v232
	v_add_u32_e32 v237, s38, v237
	s_waitcnt vmcnt(4)
	ds_write_b128 v234, v[30:33] offset:14336
	s_waitcnt lgkmcnt(7)
	v_mfma_f32_16x16x32_bf16 v[110:113], v[238:241], v[194:197], v[110:113]
	v_mfma_f32_16x16x32_bf16 v[106:109], v[242:245], v[194:197], v[106:109]
	s_waitcnt vmcnt(3)
	ds_write_b128 v234, v[34:37] offset:16384
	s_waitcnt lgkmcnt(6)
	v_mfma_f32_16x16x32_bf16 v[94:97], v[238:241], v[198:201], v[94:97]
	v_mfma_f32_16x16x32_bf16 v[90:93], v[242:245], v[198:201], v[90:93]
	s_waitcnt vmcnt(2)
	ds_write_b128 v234, v[38:41] offset:18432
	s_waitcnt lgkmcnt(5)
	v_mfma_f32_16x16x32_bf16 v[78:81], v[238:241], v[202:205], v[78:81]
	v_mfma_f32_16x16x32_bf16 v[74:77], v[242:245], v[202:205], v[74:77]
	s_waitcnt vmcnt(1)
	ds_write_b128 v234, v[42:45] offset:20480
	s_waitcnt lgkmcnt(4)
	v_mfma_f32_16x16x32_bf16 v[62:65], v[238:241], v[206:209], v[62:65]
	v_mfma_f32_16x16x32_bf16 v[58:61], v[242:245], v[206:209], v[58:61]
	s_waitcnt vmcnt(0)
	ds_write_b128 v234, v[46:49] offset:22528
	s_waitcnt lgkmcnt(0)
	s_setprio 0
	s_barrier
	s_mov_b32 s38, s35
	s_mov_b32 s35, s7
	s_mov_b32 s7, s6
	s_mov_b32 s6, s38
	ds_read_b128 v[178:181], v235 offset:16384
	ds_read_b128 v[182:185], v235 offset:17408
	ds_read_b128 v[194:197], v236
	ds_read_b128 v[198:201], v236 offset:1024
	ds_read_b128 v[202:205], v236 offset:2048
	ds_read_b128 v[206:209], v236 offset:3072
	s_waitcnt lgkmcnt(3)
	v_mfma_f32_16x16x32_bf16 v[174:177], v[178:181], v[194:197], v[174:177]
	v_mfma_f32_16x16x32_bf16 v[170:173], v[182:185], v[194:197], v[170:173]
	ds_read_b128 v[194:197], v236 offset:4096
	ds_read_b128 v[238:241], v232 offset:16384
	s_waitcnt lgkmcnt(4)
	v_mfma_f32_16x16x32_bf16 v[158:161], v[178:181], v[198:201], v[158:161]
	v_mfma_f32_16x16x32_bf16 v[154:157], v[182:185], v[198:201], v[154:157]
	ds_read_b128 v[198:201], v236 offset:5120
	ds_read_b128 v[242:245], v232 offset:17408
	s_waitcnt lgkmcnt(5)
	v_mfma_f32_16x16x32_bf16 v[142:145], v[178:181], v[202:205], v[142:145]
	v_mfma_f32_16x16x32_bf16 v[138:141], v[182:185], v[202:205], v[138:141]
	ds_read_b128 v[202:205], v236 offset:6144
	s_waitcnt lgkmcnt(5)
	v_mfma_f32_16x16x32_bf16 v[126:129], v[178:181], v[206:209], v[126:129]
	v_mfma_f32_16x16x32_bf16 v[122:125], v[182:185], v[206:209], v[122:125]
	ds_read_b128 v[206:209], v236 offset:7168
	s_sub_i32 s38, s35, s6
	v_add_u32_e32 v235, s38, v235
	v_add_u32_e32 v236, s38, v236
	s_waitcnt lgkmcnt(0)
	s_barrier
; template <int MODE>
; __device__ void gemm_tile2(const u16* __restrict__ X, int lda, const u16* __restrict__ W, int ldb, int K,
;                            int m0, int n0, u16* __restrict__ outb, int vbase,
;                            const float* resid, float* outf, unsigned char* smem) {
;     ...
;   for (int kt2 = 0; kt2 < nk; kt2 += 2) {
; #pragma unroll
;     for (int h = 0; h < 2; ++h) {
;       const int kt = kt2 + h;
;       const u16* st = sbase + h * G2STAGE;
;       bf16x8 fw[4], fx[4];
; #pragma unroll
;       for (int j = 0; j < 4; ++j) fw[j] = *(const bf16x8*)(st + 256 * G2S + (ww * 64 + j * 16 + l15) * G2S + fsw);
; #pragma unroll
;       for (int i = 0; i < 4; ++i) fx[i] = *(const bf16x8*)(st + (wx * 128 + i * 16 + l15) * G2S + fsw);
;       __builtin_amdgcn_sched_barrier(0);
;       __builtin_amdgcn_s_setprio(1);
; #pragma unroll
;       for (int i = 0; i < 4; ++i) {
; #pragma unroll
;         for (int j = 0; j < 4; ++j) {
;           if (MODE == 1) acc[i][j] = mfma16(fx[i], fw[j], acc[i][j]);
;           else acc[i][j] = mfma16(fw[j], fx[i], acc[i][j]);
;         }
;       }
;       __builtin_amdgcn_s_setprio(0);
;       __builtin_amdgcn_sched_barrier(0);
; #pragma unroll
;       for (int i = 0; i < 4; ++i) fx[i] = *(const bf16x8*)(st + (wx * 128 + (i + 4) * 16 + l15) * G2S + fsw);
;       __builtin_amdgcn_sched_barrier(0);
;       if (kt + 1 < nk) G2_LSTORE(1 - h, 1 - h);
;       if (kt + 3 < nk) G2_GLOAD(1 - h, kt + 3);
;       __builtin_amdgcn_sched_barrier(0);
;       __builtin_amdgcn_s_setprio(1);
; #pragma unroll
;       for (int i = 0; i < 4; ++i) {
; #pragma unroll
;         for (int j = 0; j < 4; ++j) {
;           if (MODE == 1) acc[i + 4][j] = mfma16(fx[i], fw[j], acc[i + 4][j]);
;           else acc[i + 4][j] = mfma16(fw[j], fx[i], acc[i + 4][j]);
;         }
;       }
;       __builtin_amdgcn_s_setprio(0);
;       __syncthreads();
;     }
	s_setprio 1
	v_mfma_f32_16x16x32_bf16 v[110:113], v[178:181], v[194:197], v[110:113]
	v_mfma_f32_16x16x32_bf16 v[106:109], v[182:185], v[194:197], v[106:109]
	ds_read_b128 v[194:197], v237
	v_mfma_f32_16x16x32_bf16 v[94:97], v[178:181], v[198:201], v[94:97]
	v_mfma_f32_16x16x32_bf16 v[90:93], v[182:185], v[198:201], v[90:93]
	ds_read_b128 v[198:201], v237 offset:1024
	v_mfma_f32_16x16x32_bf16 v[78:81], v[178:181], v[202:205], v[78:81]
	v_mfma_f32_16x16x32_bf16 v[74:77], v[182:185], v[202:205], v[74:77]
	ds_read_b128 v[202:205], v237 offset:2048
	v_mfma_f32_16x16x32_bf16 v[62:65], v[178:181], v[206:209], v[62:65]
	v_mfma_f32_16x16x32_bf16 v[58:61], v[182:185], v[206:209], v[58:61]
	ds_read_b128 v[206:209], v237 offset:3072
	s_waitcnt lgkmcnt(3)
	v_mfma_f32_16x16x32_bf16 v[174:177], v[238:241], v[194:197], v[174:177]
	v_mfma_f32_16x16x32_bf16 v[170:173], v[242:245], v[194:197], v[170:173]
	ds_read_b128 v[194:197], v237 offset:4096
	s_waitcnt lgkmcnt(3)
	v_mfma_f32_16x16x32_bf16 v[158:161], v[238:241], v[198:201], v[158:161]
	v_mfma_f32_16x16x32_bf16 v[154:157], v[242:245], v[198:201], v[154:157]
	ds_read_b128 v[198:201], v237 offset:5120
	s_waitcnt lgkmcnt(3)
	v_mfma_f32_16x16x32_bf16 v[142:145], v[238:241], v[202:205], v[142:145]
	v_mfma_f32_16x16x32_bf16 v[138:141], v[242:245], v[202:205], v[138:141]
	ds_read_b128 v[202:205], v237 offset:6144
	s_waitcnt lgkmcnt(3)
	v_mfma_f32_16x16x32_bf16 v[126:129], v[238:241], v[206:209], v[126:129]
	v_mfma_f32_16x16x32_bf16 v[122:125], v[242:245], v[206:209], v[122:125]
	ds_read_b128 v[206:209], v237 offset:7168
	s_sub_i32 s38, s6, s7
	v_add_u32_e32 v232, s38, v232
	v_add_u32_e32 v237, s38, v237
	s_waitcnt lgkmcnt(3)
	v_mfma_f32_16x16x32_bf16 v[110:113], v[238:241], v[194:197], v[110:113]
	v_mfma_f32_16x16x32_bf16 v[106:109], v[242:245], v[194:197], v[106:109]
	s_waitcnt lgkmcnt(2)
	v_mfma_f32_16x16x32_bf16 v[94:97], v[238:241], v[198:201], v[94:97]
	v_mfma_f32_16x16x32_bf16 v[90:93], v[242:245], v[198:201], v[90:93]
	s_waitcnt lgkmcnt(1)
	v_mfma_f32_16x16x32_bf16 v[78:81], v[238:241], v[202:205], v[78:81]
	v_mfma_f32_16x16x32_bf16 v[74:77], v[242:245], v[202:205], v[74:77]
	s_waitcnt lgkmcnt(0)
	v_mfma_f32_16x16x32_bf16 v[62:65], v[238:241], v[206:209], v[62:65]
	v_mfma_f32_16x16x32_bf16 v[58:61], v[242:245], v[206:209], v[58:61]
	s_setprio 0
	s_barrier
	s_mov_b32 s38, s35
	s_mov_b32 s35, s7
	s_mov_b32 s7, s6
	s_mov_b32 s6, s38
	s_nop 7
	s_branch .LBB0_320
.Lf0_none:
	v_lshrrev_b32_e32 v2, 2, v0
	v_sub_u32_e32 v2, 0, v2
	v_lshrrev_b32_e32 v3, 4, v0
	v_xor_b32_e32 v2, v3, v2
	v_lshlrev_b32_e32 v2, 4, v2
	v_and_b32_e32 v2, 48, v2
	v_lshlrev_b32_e32 v4, 6, v0
	v_and_b32_e32 v5, 0x3c0, v4
	v_bfe_u32 v6, v0, 6, 1
	v_lshl_or_b32 v6, v6, 12, v2
	v_add_u32_e32 v235, v6, v5
	v_and_b32_e32 v4, 0xffffe3c0, v4
	v_add_u32_e32 v236, v2, v4
	v_xor_b32_e32 v232, 64, v235
	v_add_u32_e32 v232, 0x6000, v232
	v_xor_b32_e32 v237, 64, v236
	v_add_u32_e32 v237, 0x6000, v237
	v_and_b32_e32 v2, 3, v0
	v_bfe_u32 v221, v0, 2, 1
	v_lshrrev_b32_e32 v4, 3, v0
	v_lshrrev_b32_e32 v5, 2, v4
	v_sub_u32_e32 v5, 0, v5
	v_and_b32_e32 v5, 3, v5
	v_xor_b32_e32 v5, v2, v5
	v_lshlrev_b32_e32 v5, 4, v5
	v_lshl_or_b32 v5, v221, 6, v5
	v_lshl_or_b32 v218, v4, 11, v5
	v_add_u32_e32 v219, 0x10000, v218
	v_lshlrev_b32_e32 v2, 4, v2
	v_xor_b32_e32 v4, v4, v221
	v_lshl_or_b32 v220, v4, 6, v2
	buffer_load_dwordx4 v[2:5], v218, s[24:27], 0 offen
	buffer_load_dwordx4 v[6:9], v219, s[24:27], 0 offen
	buffer_load_dwordx4 v[10:13], v218, s[24:27], s27 offen
	buffer_load_dwordx4 v[14:17], v219, s[24:27], s27 offen
	buffer_load_dwordx4 v[18:21], v218, s[24:27], s77 offen
	buffer_load_dwordx4 v[22:25], v219, s[24:27], s77 offen
	buffer_load_dwordx4 v[26:29], v218, s[24:27], s78 offen
	buffer_load_dwordx4 v[30:33], v219, s[24:27], s78 offen
	buffer_load_dwordx4 v[34:37], v218, s[40:43], 0 offen
	buffer_load_dwordx4 v[38:41], v219, s[40:43], 0 offen
	buffer_load_dwordx4 v[42:45], v218, s[40:43], s27 offen
	buffer_load_dwordx4 v[46:49], v219, s[40:43], s27 offen
	v_add_u32_e32 v218, 0x80, v218
	v_add_u32_e32 v219, 0x80, v219
	v_mov_b32_e32 v50, 0
	v_mov_b32_e32 v51, 0
	v_mov_b32_e32 v52, 0
	v_mov_b32_e32 v53, 0
	v_mov_b32_e32 v54, 0
	v_mov_b32_e32 v55, 0
	v_mov_b32_e32 v56, 0
	v_mov_b32_e32 v57, 0
	v_mov_b32_e32 v58, 0
	v_mov_b32_e32 v59, 0
	v_mov_b32_e32 v60, 0
	v_mov_b32_e32 v61, 0
	v_mov_b32_e32 v62, 0
	v_mov_b32_e32 v63, 0
	v_mov_b32_e32 v64, 0
	v_mov_b32_e32 v65, 0
	v_mov_b32_e32 v66, 0
	v_mov_b32_e32 v67, 0
	v_mov_b32_e32 v68, 0
	v_mov_b32_e32 v69, 0
	v_mov_b32_e32 v70, 0
	v_mov_b32_e32 v71, 0
	v_mov_b32_e32 v72, 0
	v_mov_b32_e32 v73, 0
	v_mov_b32_e32 v74, 0
	v_mov_b32_e32 v75, 0
	v_mov_b32_e32 v76, 0
	v_mov_b32_e32 v77, 0
	v_mov_b32_e32 v78, 0
	v_mov_b32_e32 v79, 0
	v_mov_b32_e32 v80, 0
	v_mov_b32_e32 v81, 0
	v_mov_b32_e32 v82, 0
	v_mov_b32_e32 v83, 0
	v_mov_b32_e32 v84, 0
	v_mov_b32_e32 v85, 0
	v_mov_b32_e32 v86, 0
	v_mov_b32_e32 v87, 0
	v_mov_b32_e32 v88, 0
	v_mov_b32_e32 v89, 0
	v_mov_b32_e32 v90, 0
	v_mov_b32_e32 v91, 0
	v_mov_b32_e32 v92, 0
	v_mov_b32_e32 v93, 0
	v_mov_b32_e32 v94, 0
	v_mov_b32_e32 v95, 0
	v_mov_b32_e32 v96, 0
	v_mov_b32_e32 v97, 0
	v_mov_b32_e32 v98, 0
	v_mov_b32_e32 v99, 0
	v_mov_b32_e32 v100, 0
	v_mov_b32_e32 v101, 0
	v_mov_b32_e32 v102, 0
	v_mov_b32_e32 v103, 0
	v_mov_b32_e32 v104, 0
	v_mov_b32_e32 v105, 0
	v_mov_b32_e32 v106, 0
	v_mov_b32_e32 v107, 0
	v_mov_b32_e32 v108, 0
	v_mov_b32_e32 v109, 0
	v_mov_b32_e32 v110, 0
	v_mov_b32_e32 v111, 0
	v_mov_b32_e32 v112, 0
	v_mov_b32_e32 v113, 0
	v_mov_b32_e32 v114, 0
	v_mov_b32_e32 v115, 0
	v_mov_b32_e32 v116, 0
	v_mov_b32_e32 v117, 0
	v_mov_b32_e32 v118, 0
	v_mov_b32_e32 v119, 0
; template <int MODE>
; __device__ void gemm_tile2(const u16* __restrict__ X, int lda, const u16* __restrict__ W, int ldb, int K,
;                            int m0, int n0, u16* __restrict__ outb, int vbase,
;                            const float* resid, float* outf, unsigned char* smem) {
;     ...
;   G2_GLOAD(0, 0);
;   G2_GLOAD(1, 1);
;   __syncthreads();
;   G2_LSTORE(0, 0);
;   G2_GLOAD(0, 2);
;   __syncthreads();
;   for (int kt2 = 0; kt2 < nk; kt2 += 2) {
; #pragma unroll
;     for (int h = 0; h < 2; ++h) {
;       const int kt = kt2 + h;
;       const u16* st = sbase + h * G2STAGE;
;       bf16x8 fw[4], fx[4];
; #pragma unroll
;       for (int j = 0; j < 4; ++j) fw[j] = *(const bf16x8*)(st + 256 * G2S + (ww * 64 + j * 16 + l15) * G2S + fsw);
; #pragma unroll
;       for (int i = 0; i < 4; ++i) fx[i] = *(const bf16x8*)(st + (wx * 128 + i * 16 + l15) * G2S + fsw);
;       __builtin_amdgcn_sched_barrier(0);
;       __builtin_amdgcn_s_setprio(1);
; #pragma unroll
;       for (int i = 0; i < 4; ++i) {
; #pragma unroll
;         for (int j = 0; j < 4; ++j) {
;           if (MODE == 1) acc[i][j] = mfma16(fx[i], fw[j], acc[i][j]);
;           else acc[i][j] = mfma16(fw[j], fx[i], acc[i][j]);
;         }
;       }
;       __builtin_amdgcn_s_setprio(0);
;       __builtin_amdgcn_sched_barrier(0);
; #pragma unroll
;       for (int i = 0; i < 4; ++i) fx[i] = *(const bf16x8*)(st + (wx * 128 + (i + 4) * 16 + l15) * G2S + fsw);
;       __builtin_amdgcn_sched_barrier(0);
;       if (kt + 1 < nk) G2_LSTORE(1 - h, 1 - h);
;       if (kt + 3 < nk) G2_GLOAD(1 - h, kt + 3);
;       __builtin_amdgcn_sched_barrier(0);
;       __builtin_amdgcn_s_setprio(1);
; #pragma unroll
;       for (int i = 0; i < 4; ++i) {
; #pragma unroll
;         for (int j = 0; j < 4; ++j) {
;           if (MODE == 1) acc[i + 4][j] = mfma16(fx[i], fw[j], acc[i + 4][j]);
;           else acc[i + 4][j] = mfma16(fw[j], fx[i], acc[i + 4][j]);
;         }
;       }
;       __builtin_amdgcn_s_setprio(0);
;       __syncthreads();
;     }
	v_mov_b32_e32 v120, 0
	v_mov_b32_e32 v121, 0
	v_mov_b32_e32 v122, 0
	v_mov_b32_e32 v123, 0
	v_mov_b32_e32 v124, 0
	v_mov_b32_e32 v125, 0
	v_mov_b32_e32 v126, 0
	v_mov_b32_e32 v127, 0
	v_mov_b32_e32 v128, 0
	v_mov_b32_e32 v129, 0
	v_mov_b32_e32 v130, 0
	v_mov_b32_e32 v131, 0
	v_mov_b32_e32 v132, 0
	v_mov_b32_e32 v133, 0
	v_mov_b32_e32 v134, 0
	v_mov_b32_e32 v135, 0
	v_mov_b32_e32 v136, 0
	v_mov_b32_e32 v137, 0
	v_mov_b32_e32 v138, 0
	v_mov_b32_e32 v139, 0
	v_mov_b32_e32 v140, 0
	v_mov_b32_e32 v141, 0
	v_mov_b32_e32 v142, 0
	v_mov_b32_e32 v143, 0
	v_mov_b32_e32 v144, 0
	v_mov_b32_e32 v145, 0
	v_mov_b32_e32 v146, 0
	v_mov_b32_e32 v147, 0
	v_mov_b32_e32 v148, 0
	v_mov_b32_e32 v149, 0
	v_mov_b32_e32 v150, 0
	v_mov_b32_e32 v151, 0
	v_mov_b32_e32 v152, 0
	v_mov_b32_e32 v153, 0
	v_mov_b32_e32 v154, 0
	v_mov_b32_e32 v155, 0
	v_mov_b32_e32 v156, 0
	v_mov_b32_e32 v157, 0
	v_mov_b32_e32 v158, 0
	v_mov_b32_e32 v159, 0
	v_mov_b32_e32 v160, 0
	v_mov_b32_e32 v161, 0
	v_mov_b32_e32 v162, 0
	v_mov_b32_e32 v163, 0
	v_mov_b32_e32 v164, 0
	v_mov_b32_e32 v165, 0
	v_mov_b32_e32 v166, 0
	v_mov_b32_e32 v167, 0
	v_mov_b32_e32 v168, 0
	v_mov_b32_e32 v169, 0
	v_mov_b32_e32 v170, 0
	v_mov_b32_e32 v171, 0
	v_mov_b32_e32 v172, 0
	v_mov_b32_e32 v173, 0
	v_mov_b32_e32 v174, 0
	v_mov_b32_e32 v175, 0
	v_mov_b32_e32 v176, 0
	v_mov_b32_e32 v177, 0
	s_mov_b32 s6, 0
	s_mov_b32 s7, 0x6000
	s_mov_b32 s35, 0xc000
	s_mov_b32 s1, 0
	v_mad_i32_i24 v234, v221, s7, v220
	s_barrier
	s_waitcnt vmcnt(11)
	ds_write_b128 v234, v[2:5]
	s_waitcnt vmcnt(10)
	ds_write_b128 v234, v[6:9] offset:2048
	s_waitcnt vmcnt(9)
	ds_write_b128 v234, v[10:13] offset:4096
	s_waitcnt vmcnt(8)
	ds_write_b128 v234, v[14:17] offset:6144
	s_waitcnt vmcnt(7)
	ds_write_b128 v234, v[18:21] offset:8192
	s_waitcnt vmcnt(6)
	ds_write_b128 v234, v[22:25] offset:10240
	s_waitcnt vmcnt(5)
	ds_write_b128 v234, v[26:29] offset:12288
	s_waitcnt vmcnt(4)
	ds_write_b128 v234, v[30:33] offset:14336
	s_waitcnt vmcnt(3)
	ds_write_b128 v234, v[34:37] offset:16384
	s_waitcnt vmcnt(2)
	ds_write_b128 v234, v[38:41] offset:18432
	s_waitcnt vmcnt(1)
	ds_write_b128 v234, v[42:45] offset:20480
	s_waitcnt vmcnt(0)
	ds_write_b128 v234, v[46:49] offset:22528
	buffer_load_dwordx4 v[2:5], v218, s[24:27], 0 offen
	buffer_load_dwordx4 v[6:9], v219, s[24:27], 0 offen
	buffer_load_dwordx4 v[10:13], v218, s[24:27], s27 offen
	buffer_load_dwordx4 v[14:17], v219, s[24:27], s27 offen
	buffer_load_dwordx4 v[18:21], v218, s[24:27], s77 offen
	buffer_load_dwordx4 v[22:25], v219, s[24:27], s77 offen
	buffer_load_dwordx4 v[26:29], v218, s[24:27], s78 offen
	buffer_load_dwordx4 v[30:33], v219, s[24:27], s78 offen
	buffer_load_dwordx4 v[34:37], v218, s[40:43], 0 offen
	buffer_load_dwordx4 v[38:41], v219, s[40:43], 0 offen
	buffer_load_dwordx4 v[42:45], v218, s[40:43], s27 offen
	buffer_load_dwordx4 v[46:49], v219, s[40:43], s27 offen
	v_add_u32_e32 v218, 0x80, v218
	v_add_u32_e32 v219, 0x80, v219
	s_waitcnt lgkmcnt(0)
	s_barrier
.Lf0n_loop:
	s_sub_i32 s38, s35, s6
	v_add_u32_e32 v235, s38, v235
	v_add_u32_e32 v236, s38, v236
	s_sub_i32 s38, s6, s35
	v_mad_i32_i24 v234, v221, s38, v220
	v_add_u32_e32 v234, s35, v234
	s_barrier
	s_setprio 1
	s_waitcnt vmcnt(11)
	ds_write_b128 v234, v[2:5]
	buffer_load_dwordx4 v[2:5], v218, s[24:27], 0 offen
	s_waitcnt vmcnt(11)
	ds_write_b128 v234, v[6:9] offset:2048
	buffer_load_dwordx4 v[6:9], v219, s[24:27], 0 offen
	s_waitcnt vmcnt(11)
	ds_write_b128 v234, v[10:13] offset:4096
	buffer_load_dwordx4 v[10:13], v218, s[24:27], s27 offen
	s_waitcnt vmcnt(11)
	ds_write_b128 v234, v[14:17] offset:6144
	buffer_load_dwordx4 v[14:17], v219, s[24:27], s27 offen
	s_waitcnt vmcnt(11)
	ds_write_b128 v234, v[18:21] offset:8192
	buffer_load_dwordx4 v[18:21], v218, s[24:27], s77 offen
	s_waitcnt vmcnt(11)
	ds_write_b128 v234, v[22:25] offset:10240
	buffer_load_dwordx4 v[22:25], v219, s[24:27], s77 offen
	s_waitcnt vmcnt(11)
	ds_write_b128 v234, v[26:29] offset:12288
	buffer_load_dwordx4 v[26:29], v218, s[24:27], s78 offen
	s_sub_i32 s38, s6, s7
	v_add_u32_e32 v232, s38, v232
	v_add_u32_e32 v237, s38, v237
	s_waitcnt vmcnt(11)
	ds_write_b128 v234, v[30:33] offset:14336
	buffer_load_dwordx4 v[30:33], v219, s[24:27], s78 offen
	s_waitcnt vmcnt(11)
	ds_write_b128 v234, v[34:37] offset:16384
	buffer_load_dwordx4 v[34:37], v218, s[40:43], 0 offen
	s_waitcnt vmcnt(11)
	ds_write_b128 v234, v[38:41] offset:18432
	buffer_load_dwordx4 v[38:41], v219, s[40:43], 0 offen
	s_waitcnt vmcnt(11)
	ds_write_b128 v234, v[42:45] offset:20480
	buffer_load_dwordx4 v[42:45], v218, s[40:43], s27 offen
	s_waitcnt vmcnt(11)
	ds_write_b128 v234, v[46:49] offset:22528
	buffer_load_dwordx4 v[46:49], v219, s[40:43], s27 offen
	v_add_u32_e32 v218, 0x80, v218
	v_add_u32_e32 v219, 0x80, v219
	s_waitcnt lgkmcnt(0)
	s_setprio 0
	s_barrier
	s_mov_b32 s38, s35
	s_mov_b32 s35, s7
	s_mov_b32 s7, s6
	s_mov_b32 s6, s38
	s_add_u32 s1, s1, 1
	s_cmp_lt_u32 s1, 14
	s_cbranch_scc1 .Lf0n_loop
	s_sub_i32 s38, s35, s6
	v_add_u32_e32 v235, s38, v235
	v_add_u32_e32 v236, s38, v236
	s_sub_i32 s38, s6, s35
	v_mad_i32_i24 v234, v221, s38, v220
	v_add_u32_e32 v234, s35, v234
	s_barrier
	s_setprio 1
	s_waitcnt vmcnt(11)
	ds_write_b128 v234, v[2:5]
	s_waitcnt vmcnt(10)
	ds_write_b128 v234, v[6:9] offset:2048
	s_waitcnt vmcnt(9)
	ds_write_b128 v234, v[10:13] offset:4096
	s_waitcnt vmcnt(8)
	ds_write_b128 v234, v[14:17] offset:6144
	s_waitcnt vmcnt(7)
	ds_write_b128 v234, v[18:21] offset:8192
	s_waitcnt vmcnt(6)
	ds_write_b128 v234, v[22:25] offset:10240
	s_waitcnt vmcnt(5)
	ds_write_b128 v234, v[26:29] offset:12288
	s_sub_i32 s38, s6, s7
	v_add_u32_e32 v232, s38, v232
	v_add_u32_e32 v237, s38, v237
	s_waitcnt vmcnt(4)
	ds_write_b128 v234, v[30:33] offset:14336
	s_waitcnt vmcnt(3)
	ds_write_b128 v234, v[34:37] offset:16384
	s_waitcnt vmcnt(2)
	ds_write_b128 v234, v[38:41] offset:18432
	s_waitcnt vmcnt(1)
	ds_write_b128 v234, v[42:45] offset:20480
	s_waitcnt vmcnt(0)
	ds_write_b128 v234, v[46:49] offset:22528
	s_waitcnt lgkmcnt(0)
	s_setprio 0
	s_barrier
	s_mov_b32 s38, s35
	s_mov_b32 s35, s7
	s_mov_b32 s7, s6
	s_mov_b32 s6, s38
	s_sub_i32 s38, s35, s6
	v_add_u32_e32 v235, s38, v235
	v_add_u32_e32 v236, s38, v236
	s_barrier
	s_setprio 1
	s_sub_i32 s38, s6, s7
	v_add_u32_e32 v232, s38, v232
	v_add_u32_e32 v237, s38, v237
	s_setprio 0
	s_barrier
	s_mov_b32 s38, s35
	s_mov_b32 s35, s7
	s_mov_b32 s7, s6
	s_mov_b32 s6, s38
	s_nop 7
	s_branch .LBB0_320
; __device__ __forceinline__ int otid() { int t = threadIdx.x; asm volatile("" : "+v"(t)); return t; }
; template <int MODE>
; __device__ void gemm_tile2(const u16* __restrict__ X, int lda, const u16* __restrict__ W, int ldb, int K,
;                            int m0, int n0, u16* __restrict__ outb, int vbase,
;                            const float* resid, float* outf, unsigned char* smem) {
;     ...
;   const int tid = otid(), lane = tid & 63, l15 = lane & 15, quad = lane >> 4;
;   const int wave = tid >> 6;
;   const int wx = wave >> 1, ww = wave & 1;
;   f32x4 acc[8][4];
; #pragma unroll
;   for (int i = 0; i < 8; ++i)
; #pragma unroll
;     for (int j = 0; j < 4; ++j) acc[i][j] = f32x4{0.f, 0.f, 0.f, 0.f};
;   u32x4 rx[2][4], rw[2][2];
;   const int lrow = tid >> 2, lkc = (tid & 3) * 8;
;   const int lsw = ((tid & 3) ^ ((0 - (lrow >> 2)) & 3)) * 8;
;   const int fsw = (quad ^ ((0 - (l15 >> 2)) & 3)) * 8;
;   const auto rsX = __builtin_amdgcn_make_buffer_rsrc((void*)(X + (size_t)m0 * lda), (short)0, 0x7fffffff, 0x00020000);
;   const auto rsW = __builtin_amdgcn_make_buffer_rsrc((void*)(W + (size_t)n0 * ldb), (short)0, 0x7fffffff, 0x00020000);
;   const int vox = (lrow * lda + lkc) * 2, vow = (lrow * ldb + lkc) * 2;
;   const int nk = K / 32;
;     ...
;   G2_GLOAD(0, 0);
;   G2_GLOAD(1, 1);
;   __syncthreads();
;   G2_LSTORE(0, 0);
;   G2_GLOAD(0, 2);
;   __syncthreads();
.Lf0_full:
	v_lshrrev_b32_e32 v2, 2, v0
	v_sub_u32_e32 v2, 0, v2
	v_lshrrev_b32_e32 v3, 4, v0
	v_xor_b32_e32 v2, v3, v2
	v_lshlrev_b32_e32 v2, 4, v2
	v_and_b32_e32 v2, 48, v2
	v_lshlrev_b32_e32 v4, 6, v0
	v_and_b32_e32 v5, 0x3c0, v4
	v_bfe_u32 v6, v0, 6, 1
	v_lshl_or_b32 v6, v6, 12, v2
	v_add_u32_e32 v235, v6, v5
	v_and_b32_e32 v4, 0xffffe3c0, v4
	v_add_u32_e32 v236, v2, v4
	v_xor_b32_e32 v232, 64, v235
	v_add_u32_e32 v232, 0x6000, v232
	v_xor_b32_e32 v237, 64, v236
	v_add_u32_e32 v237, 0x6000, v237
	v_and_b32_e32 v2, 3, v0
	v_bfe_u32 v221, v0, 2, 1
	v_lshrrev_b32_e32 v4, 3, v0
	v_lshrrev_b32_e32 v5, 2, v4
	v_sub_u32_e32 v5, 0, v5
	v_and_b32_e32 v5, 3, v5
	v_xor_b32_e32 v5, v2, v5
	v_lshlrev_b32_e32 v5, 4, v5
	v_lshl_or_b32 v5, v221, 6, v5
	v_lshl_or_b32 v218, v4, 11, v5
	v_add_u32_e32 v219, 0x10000, v218
	v_lshlrev_b32_e32 v2, 4, v2
	v_xor_b32_e32 v4, v4, v221
	v_lshl_or_b32 v220, v4, 6, v2
	buffer_load_dwordx4 v[2:5], v218, s[24:27], 0 offen
	buffer_load_dwordx4 v[6:9], v219, s[24:27], 0 offen
	buffer_load_dwordx4 v[10:13], v218, s[24:27], s27 offen
	buffer_load_dwordx4 v[14:17], v219, s[24:27], s27 offen
	buffer_load_dwordx4 v[18:21], v218, s[24:27], s77 offen
	buffer_load_dwordx4 v[22:25], v219, s[24:27], s77 offen
	buffer_load_dwordx4 v[26:29], v218, s[24:27], s78 offen
	buffer_load_dwordx4 v[30:33], v219, s[24:27], s78 offen
	buffer_load_dwordx4 v[34:37], v218, s[40:43], 0 offen
	buffer_load_dwordx4 v[38:41], v219, s[40:43], 0 offen
	buffer_load_dwordx4 v[42:45], v218, s[40:43], s27 offen
	buffer_load_dwordx4 v[46:49], v219, s[40:43], s27 offen
	v_add_u32_e32 v218, 0x80, v218
	v_add_u32_e32 v219, 0x80, v219
	v_mov_b32_e32 v50, 0
	v_mov_b32_e32 v51, 0
	v_mov_b32_e32 v52, 0
	v_mov_b32_e32 v53, 0
	v_mov_b32_e32 v54, 0
	v_mov_b32_e32 v55, 0
	v_mov_b32_e32 v56, 0
	v_mov_b32_e32 v57, 0
	v_mov_b32_e32 v58, 0
	v_mov_b32_e32 v59, 0
	v_mov_b32_e32 v60, 0
	v_mov_b32_e32 v61, 0
	v_mov_b32_e32 v62, 0
	v_mov_b32_e32 v63, 0
	v_mov_b32_e32 v64, 0
	v_mov_b32_e32 v65, 0
	v_mov_b32_e32 v66, 0
	v_mov_b32_e32 v67, 0
	v_mov_b32_e32 v68, 0
	v_mov_b32_e32 v69, 0
	v_mov_b32_e32 v70, 0
	v_mov_b32_e32 v71, 0
	v_mov_b32_e32 v72, 0
	v_mov_b32_e32 v73, 0
	v_mov_b32_e32 v74, 0
	v_mov_b32_e32 v75, 0
	v_mov_b32_e32 v76, 0
	v_mov_b32_e32 v77, 0
	v_mov_b32_e32 v78, 0
	v_mov_b32_e32 v79, 0
	v_mov_b32_e32 v80, 0
	v_mov_b32_e32 v81, 0
	v_mov_b32_e32 v82, 0
	v_mov_b32_e32 v83, 0
	v_mov_b32_e32 v84, 0
	v_mov_b32_e32 v85, 0
	v_mov_b32_e32 v86, 0
	v_mov_b32_e32 v87, 0
	v_mov_b32_e32 v88, 0
	v_mov_b32_e32 v89, 0
	v_mov_b32_e32 v90, 0
	v_mov_b32_e32 v91, 0
	v_mov_b32_e32 v92, 0
	v_mov_b32_e32 v93, 0
	v_mov_b32_e32 v94, 0
	v_mov_b32_e32 v95, 0
	v_mov_b32_e32 v96, 0
	v_mov_b32_e32 v97, 0
	v_mov_b32_e32 v98, 0
	v_mov_b32_e32 v99, 0
	v_mov_b32_e32 v100, 0
	v_mov_b32_e32 v101, 0
	v_mov_b32_e32 v102, 0
	v_mov_b32_e32 v103, 0
	v_mov_b32_e32 v104, 0
	v_mov_b32_e32 v105, 0
	v_mov_b32_e32 v106, 0
	v_mov_b32_e32 v107, 0
	v_mov_b32_e32 v108, 0
	v_mov_b32_e32 v109, 0
	v_mov_b32_e32 v110, 0
	v_mov_b32_e32 v111, 0
	v_mov_b32_e32 v112, 0
	v_mov_b32_e32 v113, 0
	v_mov_b32_e32 v114, 0
	v_mov_b32_e32 v115, 0
	v_mov_b32_e32 v116, 0
	v_mov_b32_e32 v117, 0
	v_mov_b32_e32 v118, 0
	v_mov_b32_e32 v119, 0
	v_mov_b32_e32 v120, 0
	v_mov_b32_e32 v121, 0
	v_mov_b32_e32 v122, 0
	v_mov_b32_e32 v123, 0
	v_mov_b32_e32 v124, 0
	v_mov_b32_e32 v125, 0
	v_mov_b32_e32 v126, 0
	v_mov_b32_e32 v127, 0
	v_mov_b32_e32 v128, 0
	v_mov_b32_e32 v129, 0
	v_mov_b32_e32 v130, 0
	v_mov_b32_e32 v131, 0
	v_mov_b32_e32 v132, 0
	v_mov_b32_e32 v133, 0
	v_mov_b32_e32 v134, 0
	v_mov_b32_e32 v135, 0
	v_mov_b32_e32 v136, 0
	v_mov_b32_e32 v137, 0
	v_mov_b32_e32 v138, 0
	v_mov_b32_e32 v139, 0
	v_mov_b32_e32 v140, 0
	v_mov_b32_e32 v141, 0
	v_mov_b32_e32 v142, 0
	v_mov_b32_e32 v143, 0
	v_mov_b32_e32 v144, 0
	v_mov_b32_e32 v145, 0
	v_mov_b32_e32 v146, 0
	v_mov_b32_e32 v147, 0
	v_mov_b32_e32 v148, 0
	v_mov_b32_e32 v149, 0
	v_mov_b32_e32 v150, 0
	v_mov_b32_e32 v151, 0
	v_mov_b32_e32 v152, 0
	v_mov_b32_e32 v153, 0
	v_mov_b32_e32 v154, 0
	v_mov_b32_e32 v155, 0
	v_mov_b32_e32 v156, 0
	v_mov_b32_e32 v157, 0
	v_mov_b32_e32 v158, 0
	v_mov_b32_e32 v159, 0
	v_mov_b32_e32 v160, 0
	v_mov_b32_e32 v161, 0
	v_mov_b32_e32 v162, 0
	v_mov_b32_e32 v163, 0
	v_mov_b32_e32 v164, 0
	v_mov_b32_e32 v165, 0
	v_mov_b32_e32 v166, 0
	v_mov_b32_e32 v167, 0
	v_mov_b32_e32 v168, 0
	v_mov_b32_e32 v169, 0
	v_mov_b32_e32 v170, 0
	v_mov_b32_e32 v171, 0
	v_mov_b32_e32 v172, 0
	v_mov_b32_e32 v173, 0
	v_mov_b32_e32 v174, 0
	v_mov_b32_e32 v175, 0
	v_mov_b32_e32 v176, 0
	v_mov_b32_e32 v177, 0
	s_mov_b32 s6, 0
	s_mov_b32 s7, 0x6000
	s_mov_b32 s35, 0xc000
	s_mov_b32 s1, 0
	v_mad_i32_i24 v234, v221, s7, v220
	s_barrier
	s_waitcnt vmcnt(11)
	ds_write_b128 v234, v[2:5]
	s_waitcnt vmcnt(10)
	ds_write_b128 v234, v[6:9] offset:2048
	s_waitcnt vmcnt(9)
	ds_write_b128 v234, v[10:13] offset:4096
	s_waitcnt vmcnt(8)
	ds_write_b128 v234, v[14:17] offset:6144
	s_waitcnt vmcnt(7)
	ds_write_b128 v234, v[18:21] offset:8192
	s_waitcnt vmcnt(6)
	ds_write_b128 v234, v[22:25] offset:10240
	s_waitcnt vmcnt(5)
	ds_write_b128 v234, v[26:29] offset:12288
	s_waitcnt vmcnt(4)
	ds_write_b128 v234, v[30:33] offset:14336
	s_waitcnt vmcnt(3)
	ds_write_b128 v234, v[34:37] offset:16384
	s_waitcnt vmcnt(2)
	ds_write_b128 v234, v[38:41] offset:18432
	s_waitcnt vmcnt(1)
	ds_write_b128 v234, v[42:45] offset:20480
	s_waitcnt vmcnt(0)
	ds_write_b128 v234, v[46:49] offset:22528
	buffer_load_dwordx4 v[2:5], v218, s[24:27], 0 offen
	buffer_load_dwordx4 v[6:9], v219, s[24:27], 0 offen
	buffer_load_dwordx4 v[10:13], v218, s[24:27], s27 offen
	buffer_load_dwordx4 v[14:17], v219, s[24:27], s27 offen
	buffer_load_dwordx4 v[18:21], v218, s[24:27], s77 offen
	buffer_load_dwordx4 v[22:25], v219, s[24:27], s77 offen
	buffer_load_dwordx4 v[26:29], v218, s[24:27], s78 offen
	buffer_load_dwordx4 v[30:33], v219, s[24:27], s78 offen
	buffer_load_dwordx4 v[34:37], v218, s[40:43], 0 offen
	buffer_load_dwordx4 v[38:41], v219, s[40:43], 0 offen
	buffer_load_dwordx4 v[42:45], v218, s[40:43], s27 offen
	buffer_load_dwordx4 v[46:49], v219, s[40:43], s27 offen
	v_add_u32_e32 v218, 0x80, v218
	v_add_u32_e32 v219, 0x80, v219
	s_waitcnt lgkmcnt(0)
	s_barrier
	ds_read_b128 v[178:181], v235 offset:16384
	ds_read_b128 v[182:185], v235 offset:17408
	ds_read_b128 v[186:189], v235 offset:18432
	ds_read_b128 v[190:193], v235 offset:19456
	ds_read_b128 v[194:197], v236
	ds_read_b128 v[198:201], v236 offset:1024
	ds_read_b128 v[202:205], v236 offset:2048
	ds_read_b128 v[206:209], v236 offset:3072
